# local seams: leaderless form - every workgroup adds to a per-XCC arrival word without waiting for the old value and polls it to (l+1)*nloc
# baseline (speedup 1.0000x reference)
; __device__ __forceinline__ unsigned xb_add(unsigned* p, unsigned v) { return __hip_atomic_fetch_add(p, v, __ATOMIC_RELAXED, __HIP_MEMORY_SCOPE_AGENT); }
; __device__ __forceinline__ void xcd_barrier(const XcdBarrier& b) {
;     ...
;         const unsigned old = xb_add(&bar[XB_XSUB(b.x)], 1u);
;         const unsigned gen = old / nloc;
;         if (old + 1u == (gen + 1u) * nloc) {
.LBB0_355:
	s_cmp_eq_u32 s99, 1
	s_cbranch_scc1 .Lfast_2
	s_mov_b64 s[10:11], exec
	s_lshl_b32 s8, s65, 8
	v_mbcnt_lo_u32_b32 v1, s10, 0
	s_add_u32 s8, s66, s8
	v_mbcnt_hi_u32_b32 v1, s11, v1
	s_addc_u32 s9, s67, 0
	v_cmp_eq_u32_e32 vcc, 0, v1
	s_and_saveexec_b64 s[12:13], vcc
	s_cbranch_execz .LBB0_357
	s_bcnt1_i32_b64 s10, s[10:11]
	v_mov_b32_e32 v3, 0x1000
	v_mov_b32_e32 v4, s10
	global_atomic_add v3, v3, v4, s[8:9] offset:1024 sc0

; __device__ __forceinline__ unsigned xb_ld(unsigned* p)              { return __hip_atomic_load(p, __ATOMIC_RELAXED, __HIP_MEMORY_SCOPE_AGENT); }
; __device__ __forceinline__ unsigned xb_add(unsigned* p, unsigned v) { return __hip_atomic_fetch_add(p, v, __ATOMIC_RELAXED, __HIP_MEMORY_SCOPE_AGENT); }
; #define XB_SPIN(cond, bar) do { unsigned _sp = 0; while (cond) { __builtin_amdgcn_s_sleep(1); \
;     if ((++_sp & 255u) == 0u) { if (xb_ld(&(bar)[XB_TMO])) break; if (_sp > XB_SPIN_CAP) { atomicAdd(&(bar)[XB_TMO], 1u); break; } } } } while (0)
; __device__ __forceinline__ void xcd_barrier(const XcdBarrier& b) {
;     ...
;         const unsigned old = xb_add(&bar[XB_XSUB(b.x)], 1u);
;         const unsigned gen = old / nloc;
;         if (old + 1u == (gen + 1u) * nloc) {
;             __builtin_amdgcn_fence(__ATOMIC_RELEASE, "agent");
;             asm volatile("s_waitcnt vmcnt(0)" ::: "memory");
;             const unsigned og = xb_add(&bar[XB_TOP], 1u);
;             const unsigned tg = og / nx;
;             if (og + 1u == (tg + 1u) * nx) xb_add(&bar[XB_TOPGEN], 1u);
;             else XB_SPIN(xb_ld(&bar[XB_TOPGEN]) == tg, bar);
;             __builtin_amdgcn_fence(__ATOMIC_ACQUIRE, "agent");
;             xb_add(&bar[XB_XGEN(b.x)], 1u);
;             asm volatile("s_waitcnt vmcnt(0)" ::: "memory");
;         } else {
;             XB_SPIN(xb_ld(&bar[XB_XGEN(b.x)]) == gen, bar);
;             __builtin_amdgcn_fence(__ATOMIC_ACQUIRE, "agent");
;             asm volatile("s_waitcnt vmcnt(0)" ::: "memory");
;         }
.Lfast_2:
	s_lshl_b32 s8, s65, 8
	s_add_u32 s8, s66, s8
	s_addc_u32 s9, s67, 0
	v_mov_b32_e32 v3, 0x4000
	v_mov_b32_e32 v4, 1
	global_atomic_add v3, v4, s[8:9]
	buffer_inv sc1
	v_mul_u32_u24_e32 v5, 1, v2
	s_mov_b32 s98, 0
.Lfast_poll_2:
	global_load_dword v4, v3, s[8:9] sc1
	s_waitcnt vmcnt(0)
	v_cmp_ge_u32_e32 vcc, v4, v5
	s_cbranch_vccnz .LBB0_391
	s_sleep 1
	s_add_i32 s98, s98, 1
	s_cmp_lt_u32 s98, 0x40000
	s_cbranch_scc1 .Lfast_poll_2

; __device__ __forceinline__ unsigned xb_ld(unsigned* p)              { return __hip_atomic_load(p, __ATOMIC_RELAXED, __HIP_MEMORY_SCOPE_AGENT); }
; __device__ __forceinline__ unsigned xb_add(unsigned* p, unsigned v) { return __hip_atomic_fetch_add(p, v, __ATOMIC_RELAXED, __HIP_MEMORY_SCOPE_AGENT); }
; #define XB_SPIN(cond, bar) do { unsigned _sp = 0; while (cond) { __builtin_amdgcn_s_sleep(1); \
;     if ((++_sp & 255u) == 0u) { if (xb_ld(&(bar)[XB_TMO])) break; if (_sp > XB_SPIN_CAP) { atomicAdd(&(bar)[XB_TMO], 1u); break; } } } } while (0)
; __device__ __forceinline__ void xcd_barrier(const XcdBarrier& b) {
;     ...
;         const unsigned old = xb_add(&bar[XB_XSUB(b.x)], 1u);
;         const unsigned gen = old / nloc;
;         if (old + 1u == (gen + 1u) * nloc) {
;             __builtin_amdgcn_fence(__ATOMIC_RELEASE, "agent");
;             asm volatile("s_waitcnt vmcnt(0)" ::: "memory");
;             const unsigned og = xb_add(&bar[XB_TOP], 1u);
;             const unsigned tg = og / nx;
;             if (og + 1u == (tg + 1u) * nx) xb_add(&bar[XB_TOPGEN], 1u);
;             else XB_SPIN(xb_ld(&bar[XB_TOPGEN]) == tg, bar);
;             __builtin_amdgcn_fence(__ATOMIC_ACQUIRE, "agent");
;             xb_add(&bar[XB_XGEN(b.x)], 1u);
;             asm volatile("s_waitcnt vmcnt(0)" ::: "memory");
;         } else {
;             XB_SPIN(xb_ld(&bar[XB_XGEN(b.x)]) == gen, bar);
;             __builtin_amdgcn_fence(__ATOMIC_ACQUIRE, "agent");
;             asm volatile("s_waitcnt vmcnt(0)" ::: "memory");
;         }
.Lfast_4:
	s_lshl_b32 s8, s65, 8
	s_add_u32 s8, s66, s8
	s_addc_u32 s9, s67, 0
	v_mov_b32_e32 v3, 0x4000
	v_mov_b32_e32 v4, 1
	global_atomic_add v3, v4, s[8:9]
	buffer_inv sc1
	v_mul_u32_u24_e32 v5, 2, v2
	s_mov_b32 s98, 0

; __device__ __forceinline__ unsigned xb_ld(unsigned* p)              { return __hip_atomic_load(p, __ATOMIC_RELAXED, __HIP_MEMORY_SCOPE_AGENT); }
; __device__ __forceinline__ unsigned xb_add(unsigned* p, unsigned v) { return __hip_atomic_fetch_add(p, v, __ATOMIC_RELAXED, __HIP_MEMORY_SCOPE_AGENT); }
; #define XB_SPIN(cond, bar) do { unsigned _sp = 0; while (cond) { __builtin_amdgcn_s_sleep(1); \
;     if ((++_sp & 255u) == 0u) { if (xb_ld(&(bar)[XB_TMO])) break; if (_sp > XB_SPIN_CAP) { atomicAdd(&(bar)[XB_TMO], 1u); break; } } } } while (0)
; __device__ __forceinline__ void xcd_barrier(const XcdBarrier& b) {
;     ...
;         const unsigned old = xb_add(&bar[XB_XSUB(b.x)], 1u);
;         const unsigned gen = old / nloc;
;         if (old + 1u == (gen + 1u) * nloc) {
;             __builtin_amdgcn_fence(__ATOMIC_RELEASE, "agent");
;             asm volatile("s_waitcnt vmcnt(0)" ::: "memory");
;             const unsigned og = xb_add(&bar[XB_TOP], 1u);
;             const unsigned tg = og / nx;
;             if (og + 1u == (tg + 1u) * nx) xb_add(&bar[XB_TOPGEN], 1u);
;             else XB_SPIN(xb_ld(&bar[XB_TOPGEN]) == tg, bar);
;             __builtin_amdgcn_fence(__ATOMIC_ACQUIRE, "agent");
;             xb_add(&bar[XB_XGEN(b.x)], 1u);
;             asm volatile("s_waitcnt vmcnt(0)" ::: "memory");
;         } else {
;             XB_SPIN(xb_ld(&bar[XB_XGEN(b.x)]) == gen, bar);
;             __builtin_amdgcn_fence(__ATOMIC_ACQUIRE, "agent");
;             asm volatile("s_waitcnt vmcnt(0)" ::: "memory");
;         }
.Lfast_5:
	s_lshl_b32 s8, s65, 8
	s_add_u32 s8, s66, s8
	s_addc_u32 s9, s67, 0
	v_mov_b32_e32 v3, 0x4000
	v_mov_b32_e32 v4, 1
	global_atomic_add v3, v4, s[8:9]
	buffer_inv sc1
	v_mul_u32_u24_e32 v5, 3, v2
	s_mov_b32 s98, 0

; __device__ __forceinline__ unsigned xb_ld(unsigned* p)              { return __hip_atomic_load(p, __ATOMIC_RELAXED, __HIP_MEMORY_SCOPE_AGENT); }
; __device__ __forceinline__ unsigned xb_add(unsigned* p, unsigned v) { return __hip_atomic_fetch_add(p, v, __ATOMIC_RELAXED, __HIP_MEMORY_SCOPE_AGENT); }
; #define XB_SPIN(cond, bar) do { unsigned _sp = 0; while (cond) { __builtin_amdgcn_s_sleep(1); \
;     if ((++_sp & 255u) == 0u) { if (xb_ld(&(bar)[XB_TMO])) break; if (_sp > XB_SPIN_CAP) { atomicAdd(&(bar)[XB_TMO], 1u); break; } } } } while (0)
; __device__ __forceinline__ void xcd_barrier(const XcdBarrier& b) {
;     ...
;         const unsigned old = xb_add(&bar[XB_XSUB(b.x)], 1u);
;         const unsigned gen = old / nloc;
;         if (old + 1u == (gen + 1u) * nloc) {
;             __builtin_amdgcn_fence(__ATOMIC_RELEASE, "agent");
;             asm volatile("s_waitcnt vmcnt(0)" ::: "memory");
;             const unsigned og = xb_add(&bar[XB_TOP], 1u);
;             const unsigned tg = og / nx;
;             if (og + 1u == (tg + 1u) * nx) xb_add(&bar[XB_TOPGEN], 1u);
;             else XB_SPIN(xb_ld(&bar[XB_TOPGEN]) == tg, bar);
;             __builtin_amdgcn_fence(__ATOMIC_ACQUIRE, "agent");
;             xb_add(&bar[XB_XGEN(b.x)], 1u);
;             asm volatile("s_waitcnt vmcnt(0)" ::: "memory");
;         } else {
;             XB_SPIN(xb_ld(&bar[XB_XGEN(b.x)]) == gen, bar);
;             __builtin_amdgcn_fence(__ATOMIC_ACQUIRE, "agent");
;             asm volatile("s_waitcnt vmcnt(0)" ::: "memory");
;         }
.Lfast_7:
	s_lshl_b32 s8, s65, 8
	s_add_u32 s8, s66, s8
	s_addc_u32 s9, s67, 0
	v_mov_b32_e32 v3, 0x4000
	v_mov_b32_e32 v4, 1
	global_atomic_add v3, v4, s[8:9]
	buffer_inv sc1
	v_mul_u32_u24_e32 v5, 4, v2
	s_mov_b32 s98, 0

; __device__ __forceinline__ unsigned xb_ld(unsigned* p)              { return __hip_atomic_load(p, __ATOMIC_RELAXED, __HIP_MEMORY_SCOPE_AGENT); }
; __device__ __forceinline__ unsigned xb_add(unsigned* p, unsigned v) { return __hip_atomic_fetch_add(p, v, __ATOMIC_RELAXED, __HIP_MEMORY_SCOPE_AGENT); }
; #define XB_SPIN(cond, bar) do { unsigned _sp = 0; while (cond) { __builtin_amdgcn_s_sleep(1); \
;     if ((++_sp & 255u) == 0u) { if (xb_ld(&(bar)[XB_TMO])) break; if (_sp > XB_SPIN_CAP) { atomicAdd(&(bar)[XB_TMO], 1u); break; } } } } while (0)
; __device__ __forceinline__ void xcd_barrier(const XcdBarrier& b) {
;     ...
;         const unsigned old = xb_add(&bar[XB_XSUB(b.x)], 1u);
;         const unsigned gen = old / nloc;
;         if (old + 1u == (gen + 1u) * nloc) {
;             __builtin_amdgcn_fence(__ATOMIC_RELEASE, "agent");
;             asm volatile("s_waitcnt vmcnt(0)" ::: "memory");
;             const unsigned og = xb_add(&bar[XB_TOP], 1u);
;             const unsigned tg = og / nx;
;             if (og + 1u == (tg + 1u) * nx) xb_add(&bar[XB_TOPGEN], 1u);
;             else XB_SPIN(xb_ld(&bar[XB_TOPGEN]) == tg, bar);
;             __builtin_amdgcn_fence(__ATOMIC_ACQUIRE, "agent");
;             xb_add(&bar[XB_XGEN(b.x)], 1u);
;             asm volatile("s_waitcnt vmcnt(0)" ::: "memory");
;         } else {
;             XB_SPIN(xb_ld(&bar[XB_XGEN(b.x)]) == gen, bar);
;             __builtin_amdgcn_fence(__ATOMIC_ACQUIRE, "agent");
;             asm volatile("s_waitcnt vmcnt(0)" ::: "memory");
;         }
.Lfast_8:
	s_lshl_b32 s8, s65, 8
	s_add_u32 s8, s66, s8
	s_addc_u32 s9, s67, 0
	v_mov_b32_e32 v3, 0x4000
	v_mov_b32_e32 v4, 1
	global_atomic_add v3, v4, s[8:9]
	buffer_inv sc1
	v_mul_u32_u24_e32 v5, 5, v2
	s_mov_b32 s98, 0
